# layer-1 pool/proj/w_out weight conversion moved into the tail of layer 1's in-proj GEMM; layer-1 w_in conversion split 1536/408/104 over layer 0's in-proj, projection and w_out tails
# baseline (speedup 1.0000x reference)
; __device__ __forceinline__ int launder(int v) { asm volatile("" : "+v"(v)); return v; }
; __device__ __forceinline__ void run_phase(const Params& p, int ph, LAS unsigned char* lds, const int tid, const int bid) {
;     ...
;         if (l == 0 && bid >= 40) for (int it = 1440 + bid - 40; it < 2880; it += G - 40) conv_item(p, 1, it, lds, launder(tid)); }
.LBB0_96:
	s_cmpk_lg_u32 s42, 0x100
	s_cbranch_scc1 .Ly3_old96
	s_andn2_b64 vcc, exec, s[0:1]
	s_cbranch_vccnz .LBB0_139
	s_cmp_eq_u32 s81, 6
	s_cbranch_scc0 .LBB0_139
	s_add_i32 s18, s82, 0x798
	s_cmpk_ge_i32 s18, 0x800
	s_cbranch_scc1 .LBB0_139
	s_movk_i32 s19, 0x100
	s_movk_i32 s20, 0x800
	s_mov_b32 s21, 1
	s_mov_b32 s22, 2
	s_branch .Lcva_run

; __device__ __forceinline__ int launder(int v) { asm volatile("" : "+v"(v)); return v; }
; __device__ __forceinline__ void run_phase(const Params& p, int ph, LAS unsigned char* lds, const int tid, const int bid) {
;     ...
;         if (l == 0 && bid >= 80) for (int it = bid - 80; it < 1440; it += G - 80) conv_item(p, 1, it, lds, launder(tid)); }
.Lp5_noshadow:
	s_cmp_lt_u32 s81, 7
	s_cselect_b64 s[0:1], -1, 0
	s_cmpk_gt_i32 s82, 0x4f
	s_cselect_b64 s[6:7], -1, 0
	s_cmpk_lt_u32 s82, 0x5f0
	s_cselect_b64 s[8:9], -1, 0
	s_and_b64 s[0:1], s[0:1], s[8:9]
	s_and_b64 s[0:1], s[0:1], s[6:7]
	s_andn2_b64 vcc, exec, s[0:1]
	s_cbranch_vccnz .LBB0_281
	s_add_i32 s18, s82, 0xffffffb0
	s_add_i32 s19, s42, 0xffffffb0
	s_movk_i32 s20, 0x5a0
	s_cmpk_lg_u32 s42, 0x100
	s_cbranch_scc1 .Ly3_p5old
	s_add_i32 s18, s82, 0x588
	s_movk_i32 s19, 0x88
	s_movk_i32 s20, 0x798

; __device__ __forceinline__ void run_phase(const Params& p, int ph, LAS unsigned char* lds, const int tid, const int bid) {
;     ...
;         SchedPlain S; S.init(MPAD, NIN, G, bid); S.A = pws(p) + OFF_XB; S.Bt = pws(p) + OFF_WIN + l * SZ_WIN; S.tstepA = (size_t)256 * D * 2; S.tstepB = (size_t)256 * D * 2;
;         EpiWin E; E.u = (float*)(pws(p) + OFF_U); E.zb = (bf16_t*)(pws(p) + OFF_ZB); E.rsq = (const float*)(pws(p) + OFF_RSQ) + (size_t)l * MPAD; E.cf = (const float*)(pws(p) + OFF_CS);
;         gemm_phase(lds, S, E, D, D, D, tid); }
.LBB0_581:
	s_barrier
	s_cmpk_lg_u32 s42, 0x100
	s_cbranch_scc1 .LBB0_582
	s_cmpk_lt_u32 s82, 64
	s_cbranch_scc1 .LBB0_582
	s_movk_i32 s19, 0xc0
	s_mov_b32 s21, 1
	s_mov_b32 s22, 3
	s_cmp_eq_u32 s81, 1
	s_cbranch_scc0 .Ly5_l1
	s_add_i32 s18, s82, 0xffffffc0
	s_movk_i32 s20, 0x600
	s_branch .Lcvb_run
.Ly5_l1:
	s_cmp_eq_u32 s81, 7
	s_cbranch_scc0 .LBB0_582
	s_add_i32 s18, s82, 0x7c0
	s_movk_i32 s20, 0xb40
	s_branch .Lcvb_run
